# GEMM3 start staggered by ~4us for WGs with bx&4 (shorter stagger than the 12us test); on top of v067
# baseline (speedup 1.0000x reference)
; #define fresh_tid() ((wave0 << 6) | lane_id_fresh())
; #define SEAM(k) do { if constexpr (COOP) { if (IN(k) && IN((k) + 1)) { if ((k) == CG_SEAM) cg::this_grid().sync(); else xcd_barrier(xbar, xst, lane_id_fresh() == 0 && wave0 == 0); } } } while (0)
; template <int COOP>
; __global__ void __launch_bounds__(512, 2) mega(Args a) {
;     ...
;     SEAM(5);
;     if (IN(6)) { const Ptrs P = mkptrs(ptab);
;         pg8::Gemm g{P.MG, P.WOT, T, D, D, D}; pg8::StaticOrder S; S.init(T, D, G, bx, 1, 4);
;         pg8::EpiG3 E{P.x, P.U, P.ssq, P.cnt};
;         pg8::gemm_phase(lds, g, S, E, fresh_tid());
.LBB0_541:
	s_or_b64 exec, exec, s[0:1]
	s_add_i32 s0, 0, 0x24000
	s_waitcnt lgkmcnt(0)
	v_mov_b32_e32 v0, s0
	s_barrier
	s_bitcmp1_b32 s2, 2
	s_cbranch_scc0 .Lstg6_skip
	s_sleep 127
